# diff-attn: first three V fragment LDS reads of each PV phase issued during the preceding QK MFMAs (counted lgkmcnt), PV starts without an LDS wait
# baseline (speedup 1.0000x reference)
.LBB0_385:
	s_add_i32 s93, s76, -4
	s_add_i32 s92, s72, s76
	s_add_i32 s0, s76, -1
	s_cmp_lt_u32 s0, s82
	s_cselect_b32 s78, s0, s33
	s_add_i32 s91, s76, -2
	s_cmp_lt_u32 s91, s82
	s_cselect_b32 s84, s91, s33
	s_mul_i32 s98, s78, 0x58000
	s_add_u32 s98, s100, s98
	s_addc_u32 s99, s101, 0
	s_and_b32 s0, s77, 0x6000
	s_add_i32 m0, s67, s0
	s_lshl_b64 s[0:1], s[84:85], 7
	s_add_u32 s0, s74, s0
	s_addc_u32 s1, s75, s1
	global_load_lds_dwordx4 v202, s[98:99]
	s_add_i32 s98, s2, 0xc000
	s_and_b32 s98, s98, 0xc000
	s_add_i32 s98, s67, s98
	s_add_i32 m0, s98, 0x8000
	s_nop 0
	global_load_lds_dwordx4 v204, s[0:1]
	s_add_i32 m0, s98, 0xa000
	s_add_u32 s0, s0, 0x400000
	s_addc_u32 s1, s1, 0
	global_load_lds_dwordx4 v204, s[0:1]
	s_and_b32 s0, s2, 0xc000
	s_cmp_le_u32 s93, s83
	v_add_u32_e32 v243, s0, v230
	s_cselect_b64 s[96:97], -1, 0
	s_cmp_gt_u32 s93, s83
	s_mov_b64 s[0:1], -1
	s_cbranch_scc1 .LBB0_389
	s_cmp_eq_u32 s93, 1
	s_cbranch_scc1 .Lmy_oddqk_first
	s_add_i32 s0, s77, 0xffffa000
	s_and_b32 s0, s0, 0x6000
	v_add_u32_e32 v244, s0, v229
	v_add_u32_e32 v245, v244, v232
	ds_read_b128 v[2:5], v245
	ds_read_b128 v[10:13], v241
	ds_read_b128 v[6:9], v245 offset:4096
	v_add_u32_e32 v245, v244, v234
	ds_read_b128 v[18:21], v245
	ds_read_b128 v[14:17], v241 offset:1024
	ds_read_b128 v[22:25], v245 offset:4096
	v_add_u32_e32 v245, v244, v236
	ds_read_b128 v[26:29], v245
	ds_read_b128 v[34:37], v241 offset:2048
	ds_read_b128 v[30:33], v245 offset:4096
	v_add_u32_e32 v245, v244, v238
	ds_read_b128 v[38:41], v245
	ds_read_b128 v[46:49], v241 offset:3072
	ds_read_b128 v[42:45], v245 offset:4096
	s_waitcnt lgkmcnt(10)
	v_mfma_f32_32x32x16_bf16 v[146:161], v[2:5], v[10:13], 0
	v_exp_f32_e32 v246, v50
	v_exp_f32_e32 v247, v51
	v_add_f32_e32 v242, v246, v242
	v_add_f32_e32 v242, v247, v242
	v_cvt_pk_bf16_f32 v170, v246, v247
	s_waitcnt lgkmcnt(9)
	v_mfma_f32_32x32x16_bf16 v[130:145], v[6:9], v[10:13], 0
	v_exp_f32_e32 v246, v52
	v_exp_f32_e32 v247, v53
	v_add_f32_e32 v242, v246, v242
	v_add_f32_e32 v242, v247, v242
	v_cvt_pk_bf16_f32 v171, v246, v247
	s_waitcnt lgkmcnt(7)
	v_mfma_f32_32x32x16_bf16 v[146:161], v[18:21], v[14:17], v[146:161]
	v_exp_f32_e32 v246, v54
	v_exp_f32_e32 v247, v55
	v_add_f32_e32 v242, v246, v242
	v_add_f32_e32 v242, v247, v242
	v_cvt_pk_bf16_f32 v172, v246, v247
	s_waitcnt lgkmcnt(6)
	v_mfma_f32_32x32x16_bf16 v[130:145], v[22:25], v[14:17], v[130:145]
	v_exp_f32_e32 v246, v56
	v_exp_f32_e32 v247, v57
	v_add_f32_e32 v242, v246, v242
	v_add_f32_e32 v242, v247, v242
	v_cvt_pk_bf16_f32 v173, v246, v247
	s_waitcnt lgkmcnt(4)
	v_mfma_f32_32x32x16_bf16 v[146:161], v[26:29], v[34:37], v[146:161]
	v_exp_f32_e32 v246, v58
	v_exp_f32_e32 v247, v59
	v_add_f32_e32 v242, v246, v242
	v_add_f32_e32 v242, v247, v242
	v_cvt_pk_bf16_f32 v174, v246, v247
	v_add_u32_e32 v18, v243, v233
	v_add_u32_e32 v19, v243, v235
	v_add_u32_e32 v20, v243, v237
	v_add_u32_e32 v21, v243, v239
	ds_read_b128 v[2:5], v18 offset:32768
	ds_read_b128 v[6:9], v18 offset:36864
	ds_read_b128 v[10:13], v18 offset:40960
	s_waitcnt lgkmcnt(6)
	v_mfma_f32_32x32x16_bf16 v[130:145], v[30:33], v[34:37], v[130:145]
	v_exp_f32_e32 v246, v60
	v_exp_f32_e32 v247, v61
	v_add_f32_e32 v242, v246, v242
	v_add_f32_e32 v242, v247, v242
	v_cvt_pk_bf16_f32 v175, v246, v247
	s_waitcnt lgkmcnt(4)
	v_mfma_f32_32x32x16_bf16 v[146:161], v[38:41], v[46:49], v[146:161]
	v_exp_f32_e32 v246, v62
	v_exp_f32_e32 v247, v63
	v_add_f32_e32 v242, v246, v242
	v_add_f32_e32 v242, v247, v242
	v_cvt_pk_bf16_f32 v176, v246, v247
	s_waitcnt lgkmcnt(3)
	v_mfma_f32_32x32x16_bf16 v[130:145], v[42:45], v[46:49], v[130:145]
	v_exp_f32_e32 v246, v64
	v_exp_f32_e32 v247, v65
	v_add_f32_e32 v242, v246, v242
	v_add_f32_e32 v242, v247, v242
	v_cvt_pk_bf16_f32 v177, v246, v247
	s_branch .Lmy_oddqk_join
.Lmy_oddqk_first:
	s_add_i32 s0, s77, 0xffffa000
	s_and_b32 s0, s0, 0x6000
	v_add_u32_e32 v244, s0, v229
	v_add_u32_e32 v245, v244, v232
	ds_read_b128 v[2:5], v245
	ds_read_b128 v[10:13], v241
	ds_read_b128 v[6:9], v245 offset:4096
	v_add_u32_e32 v245, v244, v234
	ds_read_b128 v[18:21], v245
	ds_read_b128 v[14:17], v241 offset:1024
	ds_read_b128 v[22:25], v245 offset:4096
	v_add_u32_e32 v245, v244, v236
	ds_read_b128 v[26:29], v245
	ds_read_b128 v[34:37], v241 offset:2048
	ds_read_b128 v[30:33], v245 offset:4096
	v_add_u32_e32 v245, v244, v238
	ds_read_b128 v[38:41], v245
	ds_read_b128 v[46:49], v241 offset:3072
	ds_read_b128 v[42:45], v245 offset:4096
	s_waitcnt lgkmcnt(10)
	v_mfma_f32_32x32x16_bf16 v[146:161], v[2:5], v[10:13], 0
	s_waitcnt lgkmcnt(9)
	v_mfma_f32_32x32x16_bf16 v[130:145], v[6:9], v[10:13], 0
	s_waitcnt lgkmcnt(7)
	v_mfma_f32_32x32x16_bf16 v[146:161], v[18:21], v[14:17], v[146:161]
	s_waitcnt lgkmcnt(6)
	v_mfma_f32_32x32x16_bf16 v[130:145], v[22:25], v[14:17], v[130:145]
	s_waitcnt lgkmcnt(4)
	v_mfma_f32_32x32x16_bf16 v[146:161], v[26:29], v[34:37], v[146:161]
	v_add_u32_e32 v18, v243, v233
	v_add_u32_e32 v19, v243, v235
	v_add_u32_e32 v20, v243, v237
	v_add_u32_e32 v21, v243, v239
	ds_read_b128 v[2:5], v18 offset:32768
	ds_read_b128 v[6:9], v18 offset:36864
	ds_read_b128 v[10:13], v18 offset:40960
	s_waitcnt lgkmcnt(6)
	v_mfma_f32_32x32x16_bf16 v[130:145], v[30:33], v[34:37], v[130:145]
	s_waitcnt lgkmcnt(4)
	v_mfma_f32_32x32x16_bf16 v[146:161], v[38:41], v[46:49], v[146:161]
	s_waitcnt lgkmcnt(3)
	v_mfma_f32_32x32x16_bf16 v[130:145], v[42:45], v[46:49], v[130:145]
	s_nop 7

.LBB0_388:
	v_exp_f32_e32 v22, v146
	s_waitcnt lgkmcnt(2)
	v_mfma_f32_32x32x16_bf16 v[114:129], v[2:5], v[162:165], v[114:129]
	ds_read_b128 v[14:17], v18 offset:45056
	v_exp_f32_e32 v23, v147
	s_waitcnt lgkmcnt(2)
	v_mfma_f32_32x32x16_bf16 v[98:113], v[6:9], v[162:165], v[98:113]
	ds_read_b128 v[2:5], v19 offset:32768
	v_add_f32_e32 v24, v22, v23
	v_cvt_pk_bf16_f32 v178, v22, v23
	v_exp_f32_e32 v22, v148
	s_waitcnt lgkmcnt(2)
	v_mfma_f32_32x32x16_bf16 v[82:97], v[10:13], v[162:165], v[82:97]
	ds_read_b128 v[6:9], v19 offset:36864
	v_exp_f32_e32 v23, v149
	s_waitcnt lgkmcnt(2)
	v_mfma_f32_32x32x16_bf16 v[66:81], v[14:17], v[162:165], v[66:81]
	ds_read_b128 v[10:13], v19 offset:40960
	v_add_f32_e32 v24, v22, v24
	v_add_f32_e32 v24, v23, v24
	v_cvt_pk_bf16_f32 v179, v22, v23
	v_exp_f32_e32 v22, v150
	s_waitcnt lgkmcnt(2)
	v_mfma_f32_32x32x16_bf16 v[114:129], v[2:5], v[166:169], v[114:129]
	ds_read_b128 v[14:17], v19 offset:45056
	v_exp_f32_e32 v23, v151
	s_waitcnt lgkmcnt(2)
	v_mfma_f32_32x32x16_bf16 v[98:113], v[6:9], v[166:169], v[98:113]
	ds_read_b128 v[2:5], v20 offset:32768
	v_add_f32_e32 v24, v22, v24
	v_add_f32_e32 v24, v23, v24
	v_cvt_pk_bf16_f32 v180, v22, v23
	v_exp_f32_e32 v22, v152
	s_waitcnt lgkmcnt(2)
	v_mfma_f32_32x32x16_bf16 v[82:97], v[10:13], v[166:169], v[82:97]
	ds_read_b128 v[6:9], v20 offset:36864
	v_exp_f32_e32 v23, v153
	s_waitcnt lgkmcnt(2)
	v_mfma_f32_32x32x16_bf16 v[66:81], v[14:17], v[166:169], v[66:81]
	ds_read_b128 v[10:13], v20 offset:40960
	v_add_f32_e32 v24, v22, v24
	v_add_f32_e32 v24, v23, v24
	v_cvt_pk_bf16_f32 v181, v22, v23
	v_exp_f32_e32 v22, v154
	s_waitcnt lgkmcnt(2)
	v_mfma_f32_32x32x16_bf16 v[114:129], v[2:5], v[170:173], v[114:129]
	ds_read_b128 v[14:17], v20 offset:45056
	v_exp_f32_e32 v23, v155
	s_waitcnt lgkmcnt(2)
	v_mfma_f32_32x32x16_bf16 v[98:113], v[6:9], v[170:173], v[98:113]
	ds_read_b128 v[2:5], v21 offset:32768
	v_add_f32_e32 v24, v22, v24
	v_add_f32_e32 v24, v23, v24
	v_cvt_pk_bf16_f32 v146, v22, v23
	v_exp_f32_e32 v22, v156
	s_waitcnt lgkmcnt(2)
	v_mfma_f32_32x32x16_bf16 v[82:97], v[10:13], v[170:173], v[82:97]
	ds_read_b128 v[6:9], v21 offset:36864
	v_exp_f32_e32 v23, v157
	s_waitcnt lgkmcnt(2)
	v_mfma_f32_32x32x16_bf16 v[66:81], v[14:17], v[170:173], v[66:81]
	ds_read_b128 v[10:13], v21 offset:40960
	v_add_f32_e32 v24, v22, v24
	v_add_f32_e32 v24, v23, v24
	v_cvt_pk_bf16_f32 v147, v22, v23
	v_exp_f32_e32 v22, v158
	s_waitcnt lgkmcnt(2)
	v_mfma_f32_32x32x16_bf16 v[114:129], v[2:5], v[174:177], v[114:129]
	ds_read_b128 v[14:17], v21 offset:45056
	v_exp_f32_e32 v23, v159
	s_waitcnt lgkmcnt(2)
	v_mfma_f32_32x32x16_bf16 v[98:113], v[6:9], v[174:177], v[98:113]
	v_add_f32_e32 v24, v22, v24
	v_add_f32_e32 v24, v23, v24
	v_cvt_pk_bf16_f32 v148, v22, v23
	v_exp_f32_e32 v22, v160
	s_waitcnt lgkmcnt(1)
	v_mfma_f32_32x32x16_bf16 v[82:97], v[10:13], v[174:177], v[82:97]
	v_exp_f32_e32 v23, v161
	s_waitcnt lgkmcnt(0)
	v_mfma_f32_32x32x16_bf16 v[66:81], v[14:17], v[174:177], v[66:81]
	v_add_f32_e32 v24, v22, v24
	v_add_f32_e32 v24, v23, v24
	v_cvt_pk_bf16_f32 v149, v22, v23
	v_add_f32_e32 v0, v242, v24
	s_mov_b64 s[0:1], 0

.LBB0_398:
	s_andn2_b64 vcc, exec, s[0:1]
	s_cbranch_vccnz .LBB0_403
	s_add_i32 s0, s77, 0xffffc000
	s_and_b32 s0, s0, 0x6000
	v_add_u32_e32 v244, s0, v229
	v_add_u32_e32 v245, v244, v232
	ds_read_b128 v[2:5], v245
	ds_read_b128 v[162:165], v241
	ds_read_b128 v[6:9], v245 offset:4096
	v_add_u32_e32 v245, v244, v234
	ds_read_b128 v[10:13], v245
	ds_read_b128 v[166:169], v241 offset:1024
	ds_read_b128 v[14:17], v245 offset:4096
	v_add_u32_e32 v245, v244, v236
	ds_read_b128 v[18:21], v245
	ds_read_b128 v[170:173], v241 offset:2048
	ds_read_b128 v[22:25], v245 offset:4096
	v_add_u32_e32 v245, v244, v238
	ds_read_b128 v[26:29], v245
	ds_read_b128 v[174:177], v241 offset:3072
	ds_read_b128 v[30:33], v245 offset:4096
	s_waitcnt lgkmcnt(10)
	v_mfma_f32_32x32x16_bf16 v[34:49], v[2:5], v[162:165], 0
	v_exp_f32_e32 v246, v130
	v_exp_f32_e32 v247, v131
	v_add_f32_e32 v0, v246, v0
	v_add_f32_e32 v0, v247, v0
	v_cvt_pk_bf16_f32 v150, v246, v247
	s_waitcnt lgkmcnt(9)
	v_mfma_f32_32x32x16_bf16 v[50:65], v[6:9], v[162:165], 0
	v_exp_f32_e32 v246, v132
	v_exp_f32_e32 v247, v133
	v_add_f32_e32 v0, v246, v0
	v_add_f32_e32 v0, v247, v0
	v_cvt_pk_bf16_f32 v151, v246, v247
	s_waitcnt lgkmcnt(7)
	v_mfma_f32_32x32x16_bf16 v[34:49], v[10:13], v[166:169], v[34:49]
	v_exp_f32_e32 v246, v134
	v_exp_f32_e32 v247, v135
	v_add_f32_e32 v0, v246, v0
	v_add_f32_e32 v0, v247, v0
	v_cvt_pk_bf16_f32 v152, v246, v247
	s_waitcnt lgkmcnt(6)
	v_mfma_f32_32x32x16_bf16 v[50:65], v[14:17], v[166:169], v[50:65]
	v_exp_f32_e32 v246, v136
	v_exp_f32_e32 v247, v137
	v_add_f32_e32 v0, v246, v0
	v_add_f32_e32 v0, v247, v0
	v_cvt_pk_bf16_f32 v153, v246, v247
	s_waitcnt lgkmcnt(4)
	v_mfma_f32_32x32x16_bf16 v[34:49], v[18:21], v[170:173], v[34:49]
	v_exp_f32_e32 v246, v138
	v_exp_f32_e32 v247, v139
	v_add_f32_e32 v0, v246, v0
	v_add_f32_e32 v0, v247, v0
	v_cvt_pk_bf16_f32 v130, v246, v247
	v_add_u32_e32 v18, v248, v233
	v_add_u32_e32 v19, v248, v235
	v_add_u32_e32 v20, v248, v237
	v_add_u32_e32 v21, v248, v239
	ds_read_b128 v[2:5], v18 offset:32768
	ds_read_b128 v[6:9], v18 offset:36864
	ds_read_b128 v[10:13], v18 offset:40960
	s_waitcnt lgkmcnt(6)
	v_mfma_f32_32x32x16_bf16 v[50:65], v[22:25], v[170:173], v[50:65]
	v_exp_f32_e32 v246, v140
	v_exp_f32_e32 v247, v141
	v_add_f32_e32 v0, v246, v0
	v_add_f32_e32 v0, v247, v0
	v_cvt_pk_bf16_f32 v131, v246, v247
	s_waitcnt lgkmcnt(4)
	v_mfma_f32_32x32x16_bf16 v[34:49], v[26:29], v[174:177], v[34:49]
	v_exp_f32_e32 v246, v142
	v_exp_f32_e32 v247, v143
	v_add_f32_e32 v0, v246, v0
	v_add_f32_e32 v0, v247, v0
	v_cvt_pk_bf16_f32 v132, v246, v247
	s_waitcnt lgkmcnt(3)
	v_mfma_f32_32x32x16_bf16 v[50:65], v[30:33], v[174:177], v[50:65]
	v_exp_f32_e32 v246, v144
	v_exp_f32_e32 v247, v145
	v_add_f32_e32 v0, v246, v0
	v_add_f32_e32 v0, v247, v0
	v_cvt_pk_bf16_f32 v133, v246, v247
	s_cmp_lg_u32 s92, 3
	s_cbranch_scc1 .LBB0_401
	v_mov_b32_e32 v25, v240
	s_nop 0
	v_cmp_gt_i32_e64 s[62:63], 22, v25
	v_cmp_gt_i32_e64 s[64:65], 23, v25
	v_cmp_gt_i32_e64 s[60:61], 21, v25
	s_and_b64 s[62:63], s[64:65], s[62:63]
	v_cmp_gt_i32_e64 s[58:59], 20, v25
	s_and_b64 s[60:61], s[62:63], s[60:61]
	v_cmp_gt_i32_e64 s[56:57], 19, v25
	s_and_b64 s[58:59], s[60:61], s[58:59]
	v_cmp_gt_i32_e64 s[54:55], 18, v25
	s_and_b64 s[56:57], s[58:59], s[56:57]
	v_cmp_gt_i32_e64 s[52:53], 17, v25
	s_and_b64 s[54:55], s[56:57], s[54:55]
	v_cmp_gt_i32_e64 s[50:51], 16, v25
	s_and_b64 s[52:53], s[54:55], s[52:53]
	v_cmp_gt_i32_e64 s[48:49], 7, v25
	s_and_b64 s[50:51], s[52:53], s[50:51]
	v_cmp_gt_i32_e64 s[46:47], 6, v25
	s_and_b64 s[48:49], s[50:51], s[48:49]
	v_cmp_gt_i32_e64 s[44:45], 5, v25
	s_and_b64 s[46:47], s[48:49], s[46:47]
	v_cmp_gt_i32_e64 s[42:43], 4, v25
	s_and_b64 s[44:45], s[46:47], s[44:45]
	v_cmp_gt_i32_e64 s[40:41], 3, v25
	s_and_b64 s[42:43], s[44:45], s[42:43]
	v_cmp_gt_i32_e64 s[38:39], 2, v25
	s_and_b64 s[40:41], s[42:43], s[40:41]
	v_cmp_gt_i32_e64 s[36:37], 1, v25
	s_and_b64 s[38:39], s[40:41], s[38:39]
	v_cmp_gt_i32_e64 s[34:35], 0, v25
	s_and_b64 s[36:37], s[38:39], s[36:37]
	s_and_b64 s[34:35], s[36:37], s[34:35]
	v_cmp_gt_i32_e64 s[30:31], 54, v25
	v_cndmask_b32_e64 v34, v34, v227, s[34:35]
	v_cmp_gt_i32_e64 s[34:35], 55, v25
	v_cmp_gt_i32_e64 s[28:29], 53, v25
	s_and_b64 s[30:31], s[34:35], s[30:31]
	v_cmp_gt_i32_e64 s[26:27], 52, v25
	s_and_b64 s[28:29], s[30:31], s[28:29]
	v_cmp_gt_i32_e64 s[24:25], 51, v25
	s_and_b64 s[26:27], s[28:29], s[26:27]
	v_cmp_gt_i32_e64 s[22:23], 50, v25
	s_and_b64 s[24:25], s[26:27], s[24:25]
	v_cmp_gt_i32_e64 s[20:21], 49, v25
	s_and_b64 s[22:23], s[24:25], s[22:23]
	v_cmp_gt_i32_e64 s[18:19], 48, v25
	s_and_b64 s[20:21], s[22:23], s[20:21]
	v_cmp_gt_i32_e64 s[16:17], 39, v25
	s_and_b64 s[18:19], s[20:21], s[18:19]
	v_cmp_gt_i32_e64 s[14:15], 38, v25
	s_and_b64 s[16:17], s[18:19], s[16:17]
	v_cmp_gt_i32_e64 s[12:13], 37, v25
	s_and_b64 s[14:15], s[16:17], s[14:15]
	v_cmp_gt_i32_e64 s[10:11], 36, v25
	s_and_b64 s[12:13], s[14:15], s[12:13]
	v_cmp_gt_i32_e64 s[8:9], 35, v25
	s_and_b64 s[10:11], s[12:13], s[10:11]
	v_cmp_gt_i32_e64 s[6:7], 34, v25
	s_and_b64 s[8:9], s[10:11], s[8:9]
	v_cmp_gt_i32_e64 s[0:1], 33, v25
	s_and_b64 s[6:7], s[8:9], s[6:7]
	v_cmp_gt_i32_e32 vcc, 32, v25
	s_and_b64 s[0:1], s[6:7], s[0:1]
	s_and_b64 vcc, s[0:1], vcc
	v_cndmask_b32_e64 v49, v49, v227, s[64:65]
	v_cndmask_b32_e64 v48, v48, v227, s[62:63]
	v_cndmask_b32_e64 v47, v47, v227, s[60:61]
	v_cndmask_b32_e64 v46, v46, v227, s[58:59]
	v_cndmask_b32_e64 v45, v45, v227, s[56:57]
	v_cndmask_b32_e64 v44, v44, v227, s[54:55]
	v_cndmask_b32_e64 v43, v43, v227, s[52:53]
	v_cndmask_b32_e64 v42, v42, v227, s[50:51]
	v_cndmask_b32_e64 v41, v41, v227, s[48:49]
	v_cndmask_b32_e64 v40, v40, v227, s[46:47]
	v_cndmask_b32_e64 v39, v39, v227, s[44:45]
	v_cndmask_b32_e64 v38, v38, v227, s[42:43]
	v_cndmask_b32_e64 v37, v37, v227, s[40:41]
	v_cndmask_b32_e64 v36, v36, v227, s[38:39]
	v_cndmask_b32_e64 v35, v35, v227, s[36:37]
	v_cndmask_b32_e64 v65, v65, v227, s[34:35]
	v_cndmask_b32_e64 v64, v64, v227, s[30:31]
	v_cndmask_b32_e64 v63, v63, v227, s[28:29]
	v_cndmask_b32_e64 v62, v62, v227, s[26:27]
	v_cndmask_b32_e64 v61, v61, v227, s[24:25]
	v_cndmask_b32_e64 v60, v60, v227, s[22:23]
	v_cndmask_b32_e64 v59, v59, v227, s[20:21]
	v_cndmask_b32_e64 v58, v58, v227, s[18:19]
	v_cndmask_b32_e64 v57, v57, v227, s[16:17]
	v_cndmask_b32_e64 v56, v56, v227, s[14:15]
	v_cndmask_b32_e64 v55, v55, v227, s[12:13]
	v_cndmask_b32_e64 v54, v54, v227, s[10:11]
	v_cndmask_b32_e64 v53, v53, v227, s[8:9]
	v_cndmask_b32_e64 v52, v52, v227, s[6:7]
	v_cndmask_b32_e64 v51, v51, v227, s[0:1]
	v_cndmask_b32_e32 v50, v50, v227, vcc
.LBB0_401:
	v_exp_f32_e32 v22, v34
	s_waitcnt lgkmcnt(2)
	v_mfma_f32_32x32x16_bf16 v[114:129], v[2:5], v[178:181], v[114:129]
	ds_read_b128 v[14:17], v18 offset:45056
	v_exp_f32_e32 v23, v35
	s_waitcnt lgkmcnt(2)
	v_mfma_f32_32x32x16_bf16 v[98:113], v[6:9], v[178:181], v[98:113]
	ds_read_b128 v[2:5], v19 offset:32768
	v_add_f32_e32 v24, v22, v23
	v_cvt_pk_bf16_f32 v162, v22, v23
	v_exp_f32_e32 v22, v36
	s_waitcnt lgkmcnt(2)
	v_mfma_f32_32x32x16_bf16 v[82:97], v[10:13], v[178:181], v[82:97]
	ds_read_b128 v[6:9], v19 offset:36864
	v_exp_f32_e32 v23, v37
	s_waitcnt lgkmcnt(2)
	v_mfma_f32_32x32x16_bf16 v[66:81], v[14:17], v[178:181], v[66:81]
	ds_read_b128 v[10:13], v19 offset:40960
	v_add_f32_e32 v24, v22, v24
	v_add_f32_e32 v24, v23, v24
	v_cvt_pk_bf16_f32 v163, v22, v23
	v_exp_f32_e32 v22, v38
	s_waitcnt lgkmcnt(2)
	v_mfma_f32_32x32x16_bf16 v[114:129], v[2:5], v[146:149], v[114:129]
	ds_read_b128 v[14:17], v19 offset:45056
	v_exp_f32_e32 v23, v39
	s_waitcnt lgkmcnt(2)
	v_mfma_f32_32x32x16_bf16 v[98:113], v[6:9], v[146:149], v[98:113]
	ds_read_b128 v[2:5], v20 offset:32768
	v_add_f32_e32 v24, v22, v24
	v_add_f32_e32 v24, v23, v24
	v_cvt_pk_bf16_f32 v164, v22, v23
	v_exp_f32_e32 v22, v40
	s_waitcnt lgkmcnt(2)
	v_mfma_f32_32x32x16_bf16 v[82:97], v[10:13], v[146:149], v[82:97]
	ds_read_b128 v[6:9], v20 offset:36864
	v_exp_f32_e32 v23, v41
	s_waitcnt lgkmcnt(2)
	v_mfma_f32_32x32x16_bf16 v[66:81], v[14:17], v[146:149], v[66:81]
	ds_read_b128 v[10:13], v20 offset:40960
	v_add_f32_e32 v24, v22, v24
	v_add_f32_e32 v24, v23, v24
	v_cvt_pk_bf16_f32 v165, v22, v23
	v_exp_f32_e32 v22, v42
	s_waitcnt lgkmcnt(2)
	v_mfma_f32_32x32x16_bf16 v[114:129], v[2:5], v[150:153], v[114:129]
	ds_read_b128 v[14:17], v20 offset:45056
	v_exp_f32_e32 v23, v43
	s_waitcnt lgkmcnt(2)
	v_mfma_f32_32x32x16_bf16 v[98:113], v[6:9], v[150:153], v[98:113]
	ds_read_b128 v[2:5], v21 offset:32768
	v_add_f32_e32 v24, v22, v24
	v_add_f32_e32 v24, v23, v24
	v_cvt_pk_bf16_f32 v166, v22, v23
	v_exp_f32_e32 v22, v44
	s_waitcnt lgkmcnt(2)
	v_mfma_f32_32x32x16_bf16 v[82:97], v[10:13], v[150:153], v[82:97]
	ds_read_b128 v[6:9], v21 offset:36864
	v_exp_f32_e32 v23, v45
	s_waitcnt lgkmcnt(2)
	v_mfma_f32_32x32x16_bf16 v[66:81], v[14:17], v[150:153], v[66:81]
	ds_read_b128 v[10:13], v21 offset:40960
	v_add_f32_e32 v24, v22, v24
	v_add_f32_e32 v24, v23, v24
	v_cvt_pk_bf16_f32 v167, v22, v23
	v_exp_f32_e32 v22, v46
	s_waitcnt lgkmcnt(2)
	v_mfma_f32_32x32x16_bf16 v[114:129], v[2:5], v[130:133], v[114:129]
	ds_read_b128 v[14:17], v21 offset:45056
	v_exp_f32_e32 v23, v47
	s_waitcnt lgkmcnt(2)
	v_mfma_f32_32x32x16_bf16 v[98:113], v[6:9], v[130:133], v[98:113]
	v_add_f32_e32 v24, v22, v24
	v_add_f32_e32 v24, v23, v24
	v_cvt_pk_bf16_f32 v168, v22, v23
	v_exp_f32_e32 v22, v48
	s_waitcnt lgkmcnt(1)
	v_mfma_f32_32x32x16_bf16 v[82:97], v[10:13], v[130:133], v[82:97]
	v_exp_f32_e32 v23, v49
	s_waitcnt lgkmcnt(0)
	v_mfma_f32_32x32x16_bf16 v[66:81], v[14:17], v[130:133], v[66:81]
	v_add_f32_e32 v24, v22, v24
	v_add_f32_e32 v24, v23, v24
	v_cvt_pk_bf16_f32 v169, v22, v23
	v_add_f32_e32 v242, v0, v24
	s_branch .LBB0_404
